# RG-LRU phase: in-tile scan LDS reads batched and gate transcendentals interleaved; wave-prefix and look-back loops read 7 / 4 granule pairs per LDS round trip
# speedup vs baseline: 1.0643x; 1.0125x over previous
.LBB0_327:
	s_or_b64 exec, exec, s[0:1]
	s_waitcnt lgkmcnt(0)
	s_barrier
	ds_read_b128 v[114:117], v147
	ds_read_b128 v[164:167], v147 offset:64
	s_waitcnt lgkmcnt(1)
	v_mfma_f32_16x16x32_bf16 v[168:171], v[114:117], v[70:73], 0
	v_add_u32_e32 v113, 0x6400, v148
	v_mov_b32_e32 v178, 1.0
	v_mfma_f32_16x16x32_bf16 v[172:175], v[114:117], v[62:65], 0
	s_waitcnt lgkmcnt(0)
	v_mfma_f32_16x16x32_bf16 v[168:171], v[164:167], v[66:69], v[168:171]
	v_mfma_f32_16x16x32_bf16 v[172:175], v[164:167], v[58:61], v[172:175]
	s_nop 7
	ds_write2_b32 v113, v168, v172 offset1:16
	ds_write2_b32 v113, v169, v173 offset0:64 offset1:80
	ds_write2_b32 v113, v170, v174 offset0:128 offset1:144
	ds_write2_b32 v113, v171, v175 offset0:192 offset1:208
	v_mfma_f32_16x16x32_bf16 v[168:171], v[114:117], v[86:89], 0
	v_mfma_f32_16x16x32_bf16 v[114:117], v[114:117], v[78:81], 0
	v_mfma_f32_16x16x32_bf16 v[168:171], v[164:167], v[82:85], v[168:171]
	v_mfma_f32_16x16x32_bf16 v[114:117], v[164:167], v[74:77], v[114:117]
	s_nop 7
	ds_write2_b32 v113, v168, v114 offset0:32 offset1:48
	ds_write2_b32 v113, v169, v115 offset0:96 offset1:112
	ds_write2_b32 v113, v170, v116 offset0:160 offset1:176
	ds_write2_b32 v113, v171, v117 offset0:224 offset1:240
	s_waitcnt lgkmcnt(0)
	s_barrier
	ds_read2st64_b32 v[198:199], v129 offset0:36 offset1:100
	ds_read2st64_b32 v[200:201], v131 offset0:36 offset1:100
	ds_read2st64_b32 v[202:203], v133 offset0:36 offset1:100
	ds_read2st64_b32 v[204:205], v135 offset0:36 offset1:100
	ds_read2st64_b32 v[206:207], v137 offset0:36 offset1:100
	ds_read2st64_b32 v[208:209], v139 offset0:36 offset1:100
	ds_read2st64_b32 v[210:211], v141 offset0:36 offset1:100
	ds_read2st64_b32 v[212:213], v143 offset0:36 offset1:100
	ds_read_b32 v214, v130 offset:41984
	ds_read_b32 v215, v132 offset:41984
	ds_read_b32 v216, v134 offset:41984
	ds_read_b32 v217, v136 offset:41984
	ds_read_b32 v218, v138 offset:41984
	ds_read_b32 v219, v140 offset:41984
	ds_read_b32 v220, v142 offset:41984
	ds_read_b32 v221, v144 offset:41984
	s_waitcnt lgkmcnt(8)
	v_add_f32_e32 v199, v153, v199
	v_add_f32_e32 v201, v153, v201
	v_add_f32_e32 v203, v153, v203
	v_add_f32_e32 v205, v153, v205
	v_add_f32_e32 v207, v153, v207
	v_add_f32_e32 v209, v153, v209
	v_add_f32_e32 v211, v153, v211
	v_add_f32_e32 v213, v153, v213
	v_mul_f32_e32 v199, 0xbfb8aa3b, v199
	v_mul_f32_e32 v201, 0xbfb8aa3b, v201
	v_mul_f32_e32 v203, 0xbfb8aa3b, v203
	v_mul_f32_e32 v205, 0xbfb8aa3b, v205
	v_mul_f32_e32 v207, 0xbfb8aa3b, v207
	v_mul_f32_e32 v209, 0xbfb8aa3b, v209
	v_mul_f32_e32 v211, 0xbfb8aa3b, v211
	v_mul_f32_e32 v213, 0xbfb8aa3b, v213
	v_exp_f32_e32 v199, v199
	v_exp_f32_e32 v201, v201
	v_exp_f32_e32 v203, v203
	v_exp_f32_e32 v205, v205
	v_exp_f32_e32 v207, v207
	v_exp_f32_e32 v209, v209
	v_exp_f32_e32 v211, v211
	v_exp_f32_e32 v213, v213
	s_waitcnt lgkmcnt(0)
	v_add_f32_e32 v214, v154, v214
	v_add_f32_e32 v215, v154, v215
	v_add_f32_e32 v216, v154, v216
	v_add_f32_e32 v217, v154, v217
	v_add_f32_e32 v218, v154, v218
	v_add_f32_e32 v219, v154, v219
	v_add_f32_e32 v220, v154, v220
	v_add_f32_e32 v221, v154, v221
	v_add_f32_e32 v199, 1.0, v199
	v_add_f32_e32 v201, 1.0, v201
	v_add_f32_e32 v203, 1.0, v203
	v_add_f32_e32 v205, 1.0, v205
	v_add_f32_e32 v207, 1.0, v207
	v_add_f32_e32 v209, 1.0, v209
	v_add_f32_e32 v211, 1.0, v211
	v_add_f32_e32 v213, 1.0, v213
	v_rcp_f32_e32 v199, v199
	v_rcp_f32_e32 v201, v201
	v_rcp_f32_e32 v203, v203
	v_rcp_f32_e32 v205, v205
	v_rcp_f32_e32 v207, v207
	v_rcp_f32_e32 v209, v209
	v_rcp_f32_e32 v211, v211
	v_rcp_f32_e32 v213, v213
	v_mul_f32_e32 v214, 0xbfb8aa3b, v214
	v_mul_f32_e32 v215, 0xbfb8aa3b, v215
	v_mul_f32_e32 v216, 0xbfb8aa3b, v216
	v_mul_f32_e32 v217, 0xbfb8aa3b, v217
	v_mul_f32_e32 v218, 0xbfb8aa3b, v218
	v_mul_f32_e32 v219, 0xbfb8aa3b, v219
	v_mul_f32_e32 v220, 0xbfb8aa3b, v220
	v_mul_f32_e32 v221, 0xbfb8aa3b, v221
	v_exp_f32_e32 v214, v214
	v_exp_f32_e32 v215, v215
	v_exp_f32_e32 v216, v216
	v_exp_f32_e32 v217, v217
	v_exp_f32_e32 v218, v218
	v_exp_f32_e32 v219, v219
	v_exp_f32_e32 v220, v220
	v_exp_f32_e32 v221, v221
	v_mul_f32_e32 v199, 0x41000000, v199
	v_mul_f32_e32 v201, 0x41000000, v201
	v_mul_f32_e32 v203, 0x41000000, v203
	v_mul_f32_e32 v205, 0x41000000, v205
	v_mul_f32_e32 v207, 0x41000000, v207
	v_mul_f32_e32 v209, 0x41000000, v209
	v_mul_f32_e32 v211, 0x41000000, v211
	v_mul_f32_e32 v213, 0x41000000, v213
	v_mul_f32_e32 v199, v155, v199
	v_mul_f32_e32 v201, v155, v201
	v_mul_f32_e32 v203, v155, v203
	v_mul_f32_e32 v205, v155, v205
	v_mul_f32_e32 v207, v155, v207
	v_mul_f32_e32 v209, v155, v209
	v_mul_f32_e32 v211, v155, v211
	v_mul_f32_e32 v213, v155, v213
	v_mul_f32_e32 v199, 0x3fb8aa3b, v199
	v_mul_f32_e32 v201, 0x3fb8aa3b, v201
	v_mul_f32_e32 v203, 0x3fb8aa3b, v203
	v_mul_f32_e32 v205, 0x3fb8aa3b, v205
	v_mul_f32_e32 v207, 0x3fb8aa3b, v207
	v_mul_f32_e32 v209, 0x3fb8aa3b, v209
	v_mul_f32_e32 v211, 0x3fb8aa3b, v211
	v_mul_f32_e32 v213, 0x3fb8aa3b, v213
	v_exp_f32_e32 v163, v199
	v_exp_f32_e32 v201, v201
	v_exp_f32_e32 v203, v203
	v_exp_f32_e32 v205, v205
	v_exp_f32_e32 v207, v207
	v_exp_f32_e32 v209, v209
	v_exp_f32_e32 v211, v211
	v_exp_f32_e32 v213, v213
	v_add_f32_e32 v214, 1.0, v214
	v_add_f32_e32 v215, 1.0, v215
	v_add_f32_e32 v216, 1.0, v216
	v_add_f32_e32 v217, 1.0, v217
	v_add_f32_e32 v218, 1.0, v218
	v_add_f32_e32 v219, 1.0, v219
	v_add_f32_e32 v220, 1.0, v220
	v_add_f32_e32 v221, 1.0, v221
	v_rcp_f32_e32 v214, v214
	v_rcp_f32_e32 v215, v215
	v_rcp_f32_e32 v216, v216
	v_rcp_f32_e32 v217, v217
	v_rcp_f32_e32 v218, v218
	v_rcp_f32_e32 v219, v219
	v_rcp_f32_e32 v220, v220
	v_rcp_f32_e32 v221, v221
	v_fma_f32 v180, -v163, v163, 1.0
	v_fma_f32 v181, -v201, v201, 1.0
	v_fma_f32 v182, -v203, v203, 1.0
	v_fma_f32 v183, -v205, v205, 1.0
	v_fma_f32 v184, -v207, v207, 1.0
	v_fma_f32 v185, -v209, v209, 1.0
	v_fma_f32 v186, -v211, v211, 1.0
	v_fma_f32 v187, -v213, v213, 1.0
	v_max_f32_e32 v180, 0, v180
	v_max_f32_e32 v181, 0, v181
	v_max_f32_e32 v182, 0, v182
	v_max_f32_e32 v183, 0, v183
	v_max_f32_e32 v184, 0, v184
	v_max_f32_e32 v185, 0, v185
	v_max_f32_e32 v186, 0, v186
	v_max_f32_e32 v187, 0, v187
	v_sqrt_f32_e32 v180, v180
	v_sqrt_f32_e32 v181, v181
	v_sqrt_f32_e32 v182, v182
	v_sqrt_f32_e32 v183, v183
	v_sqrt_f32_e32 v184, v184
	v_sqrt_f32_e32 v185, v185
	v_sqrt_f32_e32 v186, v186
	v_sqrt_f32_e32 v187, v187
	v_mul_f32_e32 v198, v198, v214
	v_mul_f32_e32 v200, v200, v215
	v_mul_f32_e32 v202, v202, v216
	v_mul_f32_e32 v204, v204, v217
	v_mul_f32_e32 v206, v206, v218
	v_mul_f32_e32 v208, v208, v219
	v_mul_f32_e32 v210, v210, v220
	v_mul_f32_e32 v212, v212, v221
	v_mul_f32_e32 v116, 0, v163
	v_fma_f32 v164, v198, v180, v116
	v_mul_f32_e32 v165, v200, v181
	v_mul_f32_e32 v166, v163, v201
	v_fmac_f32_e32 v165, v201, v164
	v_mul_f32_e32 v167, v202, v182
	v_mul_f32_e32 v169, v166, v203
	v_fmac_f32_e32 v167, v203, v165
	v_mul_f32_e32 v168, v204, v183
	v_mul_f32_e32 v171, v169, v205
	v_fmac_f32_e32 v168, v205, v167
	v_mul_f32_e32 v170, v206, v184
	v_mul_f32_e32 v173, v171, v207
	v_fmac_f32_e32 v170, v207, v168
	v_mul_f32_e32 v172, v208, v185
	v_mul_f32_e32 v175, v173, v209
	v_fmac_f32_e32 v172, v209, v170
	v_mul_f32_e32 v174, v210, v186
	v_mul_f32_e32 v176, v175, v211
	v_fmac_f32_e32 v174, v211, v172
	v_mul_f32_e32 v115, v212, v187
	v_mul_f32_e32 v114, v176, v213
	v_fmac_f32_e32 v115, v213, v174
	v_mov_b32_e32 v117, 0
	ds_write_b64 v149, v[114:115] offset:58368
	s_waitcnt lgkmcnt(0)
	s_barrier
	v_readfirstlane_b32 s68, v119
	ds_read_b64 v[226:227], v145
	ds_read_b64 v[228:229], v145 offset:512
	ds_read_b64 v[230:231], v145 offset:1024
	ds_read_b64 v[232:233], v145 offset:1536
	ds_read_b64 v[234:235], v145 offset:2048
	ds_read_b64 v[236:237], v145 offset:2560
	ds_read_b64 v[238:239], v145 offset:3072
	s_waitcnt lgkmcnt(0)
	s_cmp_lt_i32 s68, 1
	s_cbranch_scc1 .Lrnn_pfx_done
	v_mul_f32_e32 v178, v178, v226
	v_fma_f32 v117, v117, v226, v227
	s_cmp_lt_i32 s68, 2
	s_cbranch_scc1 .Lrnn_pfx_done
	v_mul_f32_e32 v178, v178, v228
	v_fma_f32 v117, v117, v228, v229
	s_cmp_lt_i32 s68, 3
	s_cbranch_scc1 .Lrnn_pfx_done
	v_mul_f32_e32 v178, v178, v230
	v_fma_f32 v117, v117, v230, v231
	s_cmp_lt_i32 s68, 4
	s_cbranch_scc1 .Lrnn_pfx_done
	v_mul_f32_e32 v178, v178, v232
	v_fma_f32 v117, v117, v232, v233
	s_cmp_lt_i32 s68, 5
	s_cbranch_scc1 .Lrnn_pfx_done
	v_mul_f32_e32 v178, v178, v234
	v_fma_f32 v117, v117, v234, v235
	s_cmp_lt_i32 s68, 6
	s_cbranch_scc1 .Lrnn_pfx_done
	v_mul_f32_e32 v178, v178, v236
	v_fma_f32 v117, v117, v236, v237
	s_cmp_lt_i32 s68, 7
	s_cbranch_scc1 .Lrnn_pfx_done
	v_mul_f32_e32 v178, v178, v238
	v_fma_f32 v117, v117, v238, v239
.Lrnn_pfx_done:
	s_cmp_lt_i32 s68, 1
	s_cbranch_scc1 .LBB0_331
	v_mul_f32_e32 v116, v163, v117
.LBB0_331:
	v_fmac_f32_e32 v115, v114, v117
	v_mul_f32_e32 v177, v114, v178
	s_and_saveexec_b64 s[0:1], s[52:53]
	s_cbranch_execz .LBB0_340
	s_add_i32 s68, s73, s33
	s_ashr_i32 s69, s68, 31
	s_lshl_b64 s[68:69], s[68:69], 12
	s_add_u32 s68, s36, s68
	v_or_b32_e32 v114, 1, v177
	s_addc_u32 s69, s37, s69
	global_store_dwordx2 v112, v[114:115], s[68:69] sc1
	s_or_b64 exec, exec, s[0:1]
	s_and_saveexec_b64 s[68:69], s[44:45]
	s_cbranch_execnz .LBB0_341

.LBB0_357:
	s_or_b64 exec, exec, s[0:1]
	s_cmp_lt_i32 s33, 1
	v_mov_b32_e32 v102, 0
	s_waitcnt lgkmcnt(0)
	s_barrier
	s_cbranch_scc1 .LBB0_306
	v_mov_b32_e32 v103, v146
	s_cmp_lt_i32 s33, 4
	s_cbranch_scc1 .Lrnn_lb_tail
.Lrnn_lb4:
	ds_read_b64 v[226:227], v103
	ds_read_b64 v[228:229], v103 offset:512
	ds_read_b64 v[230:231], v103 offset:1024
	ds_read_b64 v[232:233], v103 offset:1536
	s_add_i32 s33, s33, -4
	v_add_u32_e32 v103, 0x800, v103
	s_waitcnt lgkmcnt(3)
	v_fma_f32 v102, v102, v226, v227
	s_waitcnt lgkmcnt(2)
	v_fma_f32 v102, v102, v228, v229
	s_waitcnt lgkmcnt(1)
	v_fma_f32 v102, v102, v230, v231
	s_waitcnt lgkmcnt(0)
	v_fma_f32 v102, v102, v232, v233
	s_cmp_lt_i32 s33, 4
	s_cbranch_scc0 .Lrnn_lb4
.Lrnn_lb_tail:
	s_cmp_lt_i32 s33, 1
	s_cbranch_scc1 .LBB0_306
	ds_read_b64 v[226:227], v103
	ds_read_b64 v[228:229], v103 offset:512
	ds_read_b64 v[230:231], v103 offset:1024
	s_waitcnt lgkmcnt(0)
	v_fma_f32 v102, v102, v226, v227
	s_cmp_lt_i32 s33, 2
	s_cbranch_scc1 .LBB0_306
	v_fma_f32 v102, v102, v228, v229
	s_cmp_lt_i32 s33, 3
	s_cbranch_scc1 .LBB0_306
	v_fma_f32 v102, v102, v230, v231
	s_branch .LBB0_306
